# Wout GEMM phase: half of the workgroups (id bit 3) start ~6 us later (s_sleep 127) so the HBM-bound residual-load epilogue bursts of the two halves do not coincide
# baseline (speedup 1.0000x reference)
; #define PG8_STAGE(bufoff, gbase, voff) do { _Pragma("unroll") for (int _i = 0; _i < 2; ++_i) \
;         __builtin_amdgcn_global_load_lds((const unsigned*)((const char*)(gbase) + (voff)[_i]), (PG8_LAS unsigned*)(lds + (bufoff) + ldsw + _i * 8192), 16, 0, 0); } while (0)
; #define PG8_BAR __builtin_amdgcn_s_barrier()
; template <class Epi, class Sched, bool ALIGN_EPI = false, bool SP2 = false>
; __device__ __forceinline__ void gemm_phase(PG8_LAS unsigned char* lds, const Gemm g, const Sched& S, const Epi& E) {
;     int tid_ = threadIdx.x; asm volatile("" : "+v"(tid_));
;     const int tid = tid_, wid = __builtin_amdgcn_readfirstlane(tid >> 6), lane = tid & 63, wr = wid >> 2, wc = wid & 3, fr = lane & 15, fq = lane >> 4;
;     const int K = g.K, nt = K / BK;
;     unsigned voffA[2], voffB[2];
; #pragma unroll
;     for (int i = 0; i < 2; ++i) { int R, C; stage_rc(tid * 16 + i * 8192, R, C); const int Rb = Epi::PERM ? ((R & ~31) + perm32(R & 31)) : R;
;         voffA[i] = (unsigned)(R * K + C) * 2u; voffB[i] = (unsigned)(Rb * K + C) * 2u; }
;     ...
;     const char* cA = (const char*)g.A + (size_t)cur.pm * tstep; const char* cB = (const char*)g.Bt + (size_t)cur.pn * tstep;
;     S.a_ready(cur);
;     if constexpr (SP2) {
;         PG8_STAGE(PG8_SB(0, 0), cB, voffB); PG8_STAGE(PG8_SB(0, 1), cB + hstep, voffB); PG8_STAGE(PG8_SA(0, 0), cA, voffA); PG8_STAGE(PG8_SA(0, 1), cA + hstep, voffA);
;         if (wr == 1) PG8_BAR;
.LBB0_84:
	s_add_u32 s12, s88, 0x13d00000
	s_addc_u32 s13, s89, 0
	v_readlane_b32 s4, v254, 63
	s_mov_b64 s[0:1], -1
	s_cmp_gt_i32 s4, 4
	v_cmp_ne_u32_e64 s[4:5], 1, v189
	s_cbranch_scc0 .LBB0_122
	v_mov_b32_e32 v8, v188
	s_and_b64 vcc, exec, s[4:5]
	v_readfirstlane_b32 s18, v8
	s_cbranch_vccnz .LBB0_121
	s_bitcmp1_b32 s2, 3
	s_cbranch_scc0 .Lk5_nostag
	s_sleep 127
.Lk5_nostag:
	s_nop 0
	v_lshlrev_b32_e32 v1, 4, v8
	s_waitcnt lgkmcnt(0)
	v_add_u32_e32 v3, 0x2000, v1
	v_ashrrev_i32_e32 v2, 31, v3
	v_lshrrev_b32_e32 v2, 22, v2
	v_add_u32_e32 v2, v3, v2
	v_ashrrev_i32_e32 v2, 10, v2
	v_mul_i32_i24_e32 v4, 0x400, v2
	v_sub_u32_e32 v3, v3, v4
	v_lshrrev_b32_e32 v4, 4, v3
	v_bitop3_b32 v4, v4, v3, 32 bitop3:0x6c
	v_ashrrev_i32_e32 v3, 31, v4
	v_lshrrev_b32_e32 v3, 26, v3
	v_add_u32_e32 v5, v4, v3
	v_lshlrev_b32_e32 v6, 3, v2
	v_ashrrev_i32_e32 v3, 6, v5
	v_and_b32_e32 v6, -16, v6
	v_add_u32_e32 v6, v3, v6
	v_and_b32_e32 v7, 3, v3
	s_mov_b32 s0, 0xfffe0
	v_lshrrev_b32_e32 v9, 2, v6
	v_lshlrev_b32_e32 v10, 1, v6
	v_and_b32_e32 v5, 0xc0, v5
	v_and_or_b32 v7, v6, s0, v7
	v_and_b32_e32 v9, 4, v9
	v_and_b32_e32 v10, 24, v10
	v_sub_u32_e32 v4, v4, v5
	v_or3_b32 v7, v7, v9, v10
	v_lshlrev_b32_e32 v9, 5, v2
	v_ashrrev_i16_sdwa v4, v194, sext(v4) dst_sel:DWORD dst_unused:UNUSED_PAD src0_sel:DWORD src1_sel:BYTE_0
	v_and_b32_e32 v9, 32, v9
	v_bfe_i32 v4, v4, 0, 16
	v_add_lshl_u32 v5, v9, v4, 1
	v_lshl_add_u32 v144, v7, 12, v5
	v_lshl_add_u32 v146, v6, 12, v5
	v_bfe_i32 v5, v8, 27, 1
	v_lshrrev_b32_e32 v5, 22, v5
	v_add_u32_e32 v5, v1, v5
	v_and_b32_e32 v5, 0xfffffc00, v5
	v_sub_u32_e32 v1, v1, v5
	v_lshrrev_b32_e32 v5, 4, v1
	v_ashrrev_i32_e32 v6, 31, v8
	v_bitop3_b32 v1, v5, v1, 32 bitop3:0x6c
	v_lshrrev_b32_e32 v6, 26, v6
	v_ashrrev_i32_e32 v5, 31, v1
	v_add_u32_e32 v6, v8, v6
	v_lshrrev_b32_e32 v5, 26, v5
	v_ashrrev_i32_e32 v6, 6, v6
	v_add_u32_e32 v7, v1, v5
	v_lshlrev_b32_e32 v9, 3, v6
	v_ashrrev_i32_e32 v5, 6, v7
	v_and_b32_e32 v9, -16, v9
	v_add_u32_e32 v9, v5, v9
	v_and_b32_e32 v10, 3, v5
	v_lshrrev_b32_e32 v11, 2, v9
	v_lshlrev_b32_e32 v12, 1, v9
	v_and_b32_e32 v7, 0xc0, v7
	v_writelane_b32 v255, s4, 2
	s_ashr_i32 s28, s18, 6
	v_and_or_b32 v10, v9, s0, v10
	v_and_b32_e32 v11, 4, v11
	v_and_b32_e32 v12, 24, v12
	v_sub_u32_e32 v1, v1, v7
	v_writelane_b32 v255, s5, 3
	s_ashr_i32 s19, s18, 8
	s_lshl_b32 s4, s28, 10
	v_or3_b32 v10, v10, v11, v12
	v_lshlrev_b32_e32 v11, 5, v6
	v_ashrrev_i16_sdwa v1, v194, sext(v1) dst_sel:DWORD dst_unused:UNUSED_PAD src0_sel:DWORD src1_sel:BYTE_0
	v_readlane_b32 s0, v253, 27
	v_readlane_b32 s36, v254, 45
	v_and_b32_e32 v11, 32, v11
	v_bfe_i32 v7, v1, 0, 16
	v_readlane_b32 s1, v253, 28
	v_readlane_b32 s37, v254, 46
	s_add_u32 s58, s36, s0
	v_add_lshl_u32 v1, v11, v7, 1
	s_addc_u32 s59, s37, s1
	s_add_i32 s5, s4, 0
	v_lshl_add_u32 v148, v10, 12, v1
	s_add_i32 m0, s5, 0x10000
	v_lshl_add_u32 v150, v9, 12, v1
	global_load_lds_dwordx4 v148, s[58:59]
	s_add_i32 m0, s5, 0x12000
	s_add_u32 s0, s58, 0x80000
	global_load_lds_dwordx4 v144, s[58:59]
	s_addc_u32 s1, s59, 0
	s_add_i32 m0, s5, 0x14000
	v_writelane_b32 v255, s67, 4
	global_load_lds_dwordx4 v148, s[0:1]
	s_add_i32 m0, s5, 0x16000
	v_writelane_b32 v255, s63, 5
	global_load_lds_dwordx4 v144, s[0:1]
	v_readlane_b32 s0, v254, 4
	v_readlane_b32 s1, v254, 5
	s_add_u32 s40, s12, s0
	s_addc_u32 s41, s13, s1
	s_add_i32 s30, s5, 0x2000
	s_mov_b32 m0, s5
	s_add_u32 s0, s40, 0x80000
	global_load_lds_dwordx4 v150, s[40:41]
	s_mov_b32 m0, s30
	s_addc_u32 s1, s41, 0
	s_add_i32 s34, s5, 0x4000
	global_load_lds_dwordx4 v146, s[40:41]
	s_mov_b32 m0, s34
	s_add_i32 s57, s5, 0x6000
	global_load_lds_dwordx4 v150, s[0:1]
	s_mov_b32 m0, s57
	s_cmp_eq_u32 s19, 1
	global_load_lds_dwordx4 v146, s[0:1]
	v_writelane_b32 v255, s86, 6
	s_cselect_b64 s[0:1], -1, 0
	s_cmp_lg_u32 s19, 1
	s_cbranch_scc1 .LBB0_88
	s_barrier
